# phase 0 weight-convert loop: its four serialised tile loads issued together into separate registers with counted waits
# speedup vs baseline: 1.0045x; 1.0045x over previous
.LBB0_273:
	s_lshr_b32 s2, s3, 6
	s_sext_i32_i16 s20, s24
	v_cvt_f32_ubyte0_e32 v8, s2
	v_cvt_f32_i32_e32 v1, s20
	v_rcp_iflag_f32_e32 v9, v8
	s_ashr_i32 s21, s20, 30
	s_or_b32 s40, s21, 1
	v_mul_f32_e32 v9, v1, v9
	v_trunc_f32_e32 v9, v9
	v_fma_f32 v1, -v9, v8, v1
	v_cvt_i32_f32_e32 v9, v9
	v_cmp_ge_f32_e64 s[20:21], |v1|, v8
	s_and_b64 s[20:21], s[20:21], exec
	s_cselect_b32 s20, s40, 0
	v_readfirstlane_b32 s21, v9
	s_add_i32 s20, s21, s20
	s_sext_i32_i16 s21, s20
	s_mul_i32 s20, s20, s2
	s_sub_i32 s2, s24, s20
	s_sext_i32_i16 s20, s2
	s_lshl_b32 s20, s20, 6
	s_lshl_b32 s2, s21, 6
	s_ashr_i32 s21, s20, 31
	s_lshl_b64 s[40:41], s[20:21], 2
	s_add_u32 s38, s38, s40
	v_add_u32_e32 v1, s2, v4
	s_addc_u32 s39, s39, s41
	v_lshl_add_u64 v[8:9], s[38:39], 0, v[2:3]
	v_mad_i64_i32 v[10:11], s[38:39], v1, s3, 0
	v_add_u32_e32 v12, 16, v1
	v_add_u32_e32 v14, 32, v1
	v_add_u32_e32 v1, 48, v1
	v_lshl_add_u64 v[10:11], v[10:11], 2, v[8:9]
	v_mad_i64_i32 v[12:13], s[38:39], v12, s3, 0
	v_mad_i64_i32 v[14:15], s[38:39], v14, s3, 0
	v_mad_i64_i32 v[16:17], s[38:39], v1, s3, 0
	v_lshl_add_u64 v[12:13], v[12:13], 2, v[8:9]
	v_lshl_add_u64 v[14:15], v[14:15], 2, v[8:9]
	v_lshl_add_u64 v[16:17], v[16:17], 2, v[8:9]
	global_load_dwordx4 v[8:11], v[10:11], off
	global_load_dwordx4 v[20:23], v[12:13], off
	global_load_dwordx4 v[24:27], v[14:15], off
	global_load_dwordx4 v[28:31], v[16:17], off
	v_add_u32_e32 v1, 0x1040, v7
	s_ashr_i32 s3, s2, 31
	s_waitcnt vmcnt(3)
	ds_write2_b32 v7, v8, v9 offset1:1
	ds_write2_b32 v7, v10, v11 offset0:2 offset1:3
	s_waitcnt vmcnt(2)
	ds_write2_b32 v1, v20, v21 offset1:1
	v_add_u32_e32 v1, 0x1048, v7
	ds_write2_b32 v1, v22, v23 offset1:1
	v_add_u32_e32 v1, 0x2080, v7
	s_waitcnt vmcnt(1)
	ds_write2_b32 v1, v24, v25 offset1:1
	v_add_u32_e32 v1, 0x2088, v7
	ds_write2_b32 v1, v26, v27 offset1:1
	v_add_u32_e32 v1, 0x30c0, v7
	s_waitcnt vmcnt(0)
	ds_write2_b32 v1, v28, v29 offset1:1
	v_add_u32_e32 v1, 0x30c8, v7
	ds_write2_b32 v1, v30, v31 offset1:1
	s_waitcnt lgkmcnt(0)
	s_barrier
	ds_read2_b32 v[8:9], v6 offset1:65
	ds_read2_b32 v[10:11], v6 offset0:130 offset1:195
	v_add_u32_e32 v1, 0x400, v6
	ds_read2_b32 v[12:13], v1 offset0:134 offset1:199
	s_waitcnt lgkmcnt(2)
	v_cvt_pk_bf16_f32 v8, v8, v9
	s_waitcnt lgkmcnt(1)
	v_cvt_pk_bf16_f32 v9, v10, v11
	ds_read2_b32 v[10:11], v1 offset0:4 offset1:69
	v_add_u32_e32 v1, 0x800, v6
	ds_read2_b32 v[14:15], v1 offset0:138 offset1:203
	s_waitcnt lgkmcnt(1)
	v_cvt_pk_bf16_f32 v10, v10, v11
	v_cvt_pk_bf16_f32 v11, v12, v13
	ds_read2_b32 v[12:13], v1 offset0:8 offset1:73
	v_add_u32_e32 v1, 0xc00, v6
	ds_read2_b32 v[16:17], v1 offset0:142 offset1:207
	s_waitcnt lgkmcnt(1)
	v_cvt_pk_bf16_f32 v12, v12, v13
	v_cvt_pk_bf16_f32 v13, v14, v15
	ds_read2_b32 v[14:15], v1 offset0:12 offset1:77
	v_mov_b32_e32 v1, v3
	s_waitcnt lgkmcnt(0)
	v_cvt_pk_bf16_f32 v14, v14, v15
	v_cvt_pk_bf16_f32 v15, v16, v17
	v_add_u32_e32 v16, s20, v5
	v_ashrrev_i32_e32 v17, 31, v16
	v_lshlrev_b64 v[16:17], 11, v[16:17]
	v_lshl_add_u64 v[16:17], s[0:1], 0, v[16:17]
	v_lshl_add_u64 v[16:17], s[2:3], 1, v[16:17]
	v_readlane_b32 s0, v253, 39
	v_lshl_add_u64 v[16:17], v[16:17], 0, v[0:1]
	v_readlane_b32 s1, v253, 40
	global_store_dwordx4 v[16:17], v[8:11], off
	global_store_dwordx4 v[16:17], v[12:15], off offset:16
	s_barrier
	s_load_dword s0, s[0:1], 0x0
	s_waitcnt lgkmcnt(0)
	s_add_i32 s88, s88, s0
	s_cmpk_gt_i32 s88, 0x147f
	s_cbranch_scc1 .LBB0_278
